# statically placed scan blocks leave the phase-C queue loop directly after their item (guarded on grid==512)
# speedup vs baseline: 1.0440x; 1.0147x over previous
; __device__ __forceinline__ unsigned char* WS(const Params& p) { unsigned z = 0; asm volatile("" : "+s"(z)); return p.ws + z; }
; __device__ __forceinline__ int opaque_tid() { int t = threadIdx.x; asm volatile("" : "+v"(t)); return t; }
; __device__ __forceinline__ void run_phase(const Params& p, int ph, char* lds, int mode) {
;     ...
;       int* sh = (int*)(lds + 74240);
;       for (;;) {
;         __syncthreads();
;         if (opaque_tid() == 0) *sh = (int)atomicAdd(ctr, 1u);
;         __syncthreads();
;         int it = *sh;
;         if (mode == 1) { if (it >= 192) break; }
;         else if (mode == 2) { if (it >= 512) break; it += 208; }
;         const int ntot = 192 + 16 + 512 + 1024 + N_CONV_FFN + (l == 0 ? N_CONV_MIX : 0);
;         if (it >= ntot) break;
;         unsigned* flags = (unsigned*)(WS(p) + OFF_CTRL) + 16 + l * 16;
;         if (it < 192) { if (EN(20)) rwkv_scan2_item(p, it, lds); }
;         else if (it < 208) { if (EN(21)) ml_p2_item(p, it - 192, flags + (it - 192), lds); }
;         else if (it < 720) { const int a = it - 208; if (EN(22)) attn_item(p, l, a & 15, 31 - (a >> 4), lds); }
;         else if (mode != 0) { }
;         else if (it < 1744) { if (EN(30)) ml_p3_item(p, l, it - 720, flags + ((it - 720) >> 6), lds); }
;         else if (it < 1744 + N_CONV_FFN) { if (EN(41)) conv_ffn(p, l, it - 1744, lds); }
;         else conv_mixer(p, 1, it - 1744 - N_CONV_FFN, lds);
;       }
.Lsc_done:
	s_waitcnt vmcnt(0) lgkmcnt(0)
	v_readlane_b32 s2, v255, 45
	s_nop 0
	s_cmp_eq_u32 s2, 0
	s_cbranch_scc1 .LBB0_157
	s_mov_b64 s[24:25], -1
	s_branch .LBB0_158
